# final RMSNorm row loop software-pipelined (prefetch next row, counted vmcnt past the stores)
# baseline (speedup 1.0000x reference)
; __device__ __forceinline__ float bf_lo(unsigned w) { return __uint_as_float(w << 16); }
; __device__ __forceinline__ float bf_hi(unsigned w) { return __uint_as_float(w & 0xffff0000u); }
; template <int MODE, bool INBF> ...
;     ...
;         for (int i0 = 0; i0 < 8; i0 += RB) {
;             f32x4 v[RB][8];
; #pragma unroll
;             for (int q = 0; q < RB; ++q) { const int row = blk * 64 + wave + 8 * (i0 + q);
;                 if (INBF) { const u32x2* xr = (const u32x2*)((const bf16*)xin_ + (size_t)row * DM) + lane;
; #pragma unroll
;                     for (int j = 0; j < 8; ++j) { const u32x2 w = xr[64 * j]; v[q][j] = (f32x4){bf_lo(w.x), bf_hi(w.x), bf_lo(w.y), bf_hi(w.y)}; }
;                 } else { const f32x4* xr = (const f32x4*)((const float*)xin_ + (size_t)row * DM) + lane;
; #pragma unroll
;                     for (int j = 0; j < 8; ++j) v[q][j] = xr[64 * j]; } }
; #pragma unroll
;             for (int q = 0; q < RB; ++q) { const int row = blk * 64 + wave + 8 * (i0 + q); float ss = 0.f;
; #pragma unroll
;                 for (int j = 0; j < 8; ++j) ss += (v[q][j].x * v[q][j].x + v[q][j].y * v[q][j].y) + (v[q][j].z * v[q][j].z + v[q][j].w * v[q][j].w);
;                 const float rstd = 1.0f / sqrtf(wave_sum(ss) * (1.0f / DM) + EPS);
.LBB0_1326:
	s_or_b64 exec, exec, s[12:13]
	s_ashr_i32 s15, s14, 31
	s_lshl_b64 s[12:13], s[14:15], 13
	v_lshl_add_u64 v[26:27], v[22:23], 0, s[12:13]
	v_lshl_add_u64 v[28:29], v[24:25], 0, s[12:13]
	s_mov_b64 s[20:21], 0
	s_waitcnt lgkmcnt(0)
	s_barrier
	v_lshl_add_u64 v[232:233], v[28:29], 0, s[20:21]
	v_add_co_u32_e32 v232, vcc, 0x10401000, v232
	s_nop 1
	v_addc_co_u32_e32 v233, vcc, 0, v233, vcc
	global_load_dwordx4 v[200:203], v[232:233], off offset:-4096
	global_load_dwordx4 v[204:207], v[232:233], off offset:-3072
	global_load_dwordx4 v[208:211], v[232:233], off offset:-2048
	global_load_dwordx4 v[212:215], v[232:233], off offset:-1024
	global_load_dwordx4 v[216:219], v[232:233], off
	global_load_dwordx4 v[220:223], v[232:233], off offset:1024
	global_load_dwordx4 v[224:227], v[232:233], off offset:3072
	global_load_dwordx4 v[228:231], v[232:233], off offset:2048
	s_waitcnt vmcnt(0)
.LBB0_1327:
	v_lshl_add_u64 v[30:31], v[28:29], 0, s[20:21]
	v_add_co_u32_e32 v106, vcc, 0x10400000, v30
	ds_read_b128 v[0:3], v38
	ds_read_b128 v[4:7], v38 offset:1024
	ds_read_b128 v[12:15], v38 offset:8192
	ds_read_b128 v[8:11], v38 offset:9216
	ds_read_b128 v[16:19], v38 offset:2048
	ds_read_b128 v[46:49], v38 offset:3072
	ds_read_b128 v[50:53], v38 offset:10240
	ds_read_b128 v[54:57], v38 offset:11264
	ds_read_b128 v[58:61], v38 offset:4096
	ds_read_b128 v[62:65], v38 offset:5120
	ds_read_b128 v[66:69], v38 offset:12288
	ds_read_b128 v[70:73], v38 offset:13312
	ds_read_b128 v[74:77], v38 offset:6144
	ds_read_b128 v[78:81], v38 offset:7168
	ds_read_b128 v[82:85], v38 offset:14336
	ds_read_b128 v[86:89], v38 offset:15360
	v_addc_co_u32_e32 v107, vcc, 0, v31, vcc
	s_nop 0
	s_nop 0
	s_nop 0
	s_nop 0
	v_add_co_u32_e32 v30, vcc, 0x10401000, v30
	v_lshl_add_u64 v[122:123], v[26:27], 0, s[20:21]
	s_nop 0
	v_addc_co_u32_e32 v31, vcc, 0, v31, vcc
	s_nop 0
	s_nop 0
	s_nop 0
	s_nop 0
	s_add_u32 s20, s20, 0x10000
	s_addc_u32 s21, s21, 0
	s_cmp_lg_u32 s20, 0x80000
	s_waitcnt vmcnt(8) lgkmcnt(0)
	v_mov_b32_e32 v90, v200
	v_mov_b32_e32 v91, v201
	v_mov_b32_e32 v92, v202
	v_mov_b32_e32 v93, v203
	v_mov_b32_e32 v94, v204
	v_mov_b32_e32 v95, v205
	v_mov_b32_e32 v96, v206
	v_mov_b32_e32 v97, v207
	v_mov_b32_e32 v98, v208
	v_mov_b32_e32 v99, v209
	v_mov_b32_e32 v100, v210
	v_mov_b32_e32 v101, v211
	v_mov_b32_e32 v102, v212
	v_mov_b32_e32 v103, v213
	v_mov_b32_e32 v104, v214
	v_mov_b32_e32 v105, v215
	v_mov_b32_e32 v106, v216
	v_mov_b32_e32 v107, v217
	v_mov_b32_e32 v108, v218
	v_mov_b32_e32 v109, v219
	v_mov_b32_e32 v110, v220
	v_mov_b32_e32 v111, v221
	v_mov_b32_e32 v112, v222
	v_mov_b32_e32 v113, v223
	v_mov_b32_e32 v114, v224
	v_mov_b32_e32 v115, v225
	v_mov_b32_e32 v116, v226
	v_mov_b32_e32 v117, v227
	v_mov_b32_e32 v118, v228
	v_mov_b32_e32 v119, v229
	v_mov_b32_e32 v120, v230
	v_mov_b32_e32 v121, v231
	s_cbranch_scc0 .Lnp_skip_nF
	v_lshl_add_u64 v[232:233], v[28:29], 0, s[20:21]
	v_add_co_u32_e32 v232, vcc, 0x10401000, v232
	s_nop 1
	v_addc_co_u32_e32 v233, vcc, 0, v233, vcc
	global_load_dwordx4 v[200:203], v[232:233], off offset:-4096
	global_load_dwordx4 v[204:207], v[232:233], off offset:-3072
	global_load_dwordx4 v[208:211], v[232:233], off offset:-2048
	global_load_dwordx4 v[212:215], v[232:233], off offset:-1024
	global_load_dwordx4 v[216:219], v[232:233], off
	global_load_dwordx4 v[220:223], v[232:233], off offset:1024
	global_load_dwordx4 v[224:227], v[232:233], off offset:3072
	global_load_dwordx4 v[228:231], v[232:233], off offset:2048
; #define LAS __attribute__((address_space(3)))
; template <int MODE, bool INBF> ...
;     ...
;             for (int q = 0; q < RB; ++q) { const int row = blk * 64 + wave + 8 * (i0 + q); float ss = 0.f;
; #pragma unroll
;                 for (int j = 0; j < 8; ++j) ss += (v[q][j].x * v[q][j].x + v[q][j].y * v[q][j].y) + (v[q][j].z * v[q][j].z + v[q][j].w * v[q][j].w);
;                 const float rstd = 1.0f / sqrtf(wave_sum(ss) * (1.0f / DM) + EPS);
; #pragma unroll
;                 for (int j = 0; j < 8; ++j) { const f32x4 a = *(const LAS f32x4*)(cA + 4 * (64 * j + lane)), bb = *(const LAS f32x4*)(cB + 4 * (64 * j + lane)); v[q][j] = (v[q][j] * rstd) * a + bb; }
;                 if (MODE == 1) { f32x4* o = (f32x4*)(outf + (size_t)row * DM) + lane;
; #pragma unroll
;                     for (int j = 0; j < 8; ++j) o[64 * j] = v[q][j];
.Lnp_skip_nF:
	v_mov_b32_e32 v124, v91
	v_mov_b32_e32 v125, v95
	v_mov_b32_e32 v128, v93
	v_mov_b32_e32 v129, v97
	v_mov_b32_e32 v30, v90
	v_mov_b32_e32 v31, v94
	v_mov_b32_e32 v126, v92
	v_mov_b32_e32 v127, v96
	v_pk_mul_f32 v[130:131], v[100:101], v[100:101]
	v_pk_mul_f32 v[132:133], v[98:99], v[98:99]
	v_pk_mul_f32 v[124:125], v[124:125], v[124:125]
	v_pk_mul_f32 v[128:129], v[128:129], v[128:129]
	v_pk_mov_b32 v[138:139], v[132:133], v[130:131] op_sel:[1,0]
	v_mov_b32_e32 v133, v131
	v_pk_fma_f32 v[30:31], v[30:31], v[30:31], v[124:125]
	v_pk_fma_f32 v[124:125], v[126:127], v[126:127], v[128:129]
	v_mul_f32_e32 v134, v103, v103
	v_mul_f32_e32 v136, v105, v105
	v_pk_add_f32 v[126:127], v[138:139], v[132:133]
	v_pk_add_f32 v[30:31], v[30:31], v[124:125]
	v_mul_f32_e32 v45, v106, v106
	v_mul_f32_e32 v143, v107, v107
	v_mul_f32_e32 v145, v108, v108
	v_mul_f32_e32 v146, v109, v109
	v_pk_fma_f32 v[130:131], v[102:103], v[102:103], v[134:135] op_sel_hi:[1,1,0]
	v_pk_fma_f32 v[134:135], v[104:105], v[104:105], v[136:137] op_sel_hi:[1,1,0]
	v_pk_add_f32 v[124:125], v[126:127], v[126:127] op_sel:[0,1] op_sel_hi:[1,0]
	v_pk_add_f32 v[30:31], v[30:31], v[30:31] op_sel:[0,1] op_sel_hi:[1,0]
	v_pk_mul_f32 v[136:137], v[112:113], v[112:113]
	v_pk_mul_f32 v[140:141], v[110:111], v[110:111]
	v_mov_b32_e32 v131, v145
	v_mov_b32_e32 v135, v146
	v_mov_b32_e32 v125, v143
	v_mov_b32_e32 v31, v45
	v_pk_mov_b32 v[128:129], v[140:141], v[136:137] op_sel:[1,0]
	v_mov_b32_e32 v141, v137
	v_pk_add_f32 v[126:127], v[130:131], v[134:135]
	v_pk_add_f32 v[30:31], v[30:31], v[124:125]
	v_mul_f32_e32 v142, v119, v119
	v_mul_f32_e32 v144, v121, v121
	v_pk_add_f32 v[128:129], v[128:129], v[140:141]
	v_pk_add_f32 v[30:31], v[30:31], v[126:127]
	v_mul_f32_e32 v147, v114, v114
	v_mul_f32_e32 v148, v115, v115
	v_mul_f32_e32 v149, v116, v116
	v_mul_f32_e32 v150, v117, v117
	v_pk_fma_f32 v[132:133], v[118:119], v[118:119], v[142:143] op_sel_hi:[1,1,0]
	v_pk_fma_f32 v[136:137], v[120:121], v[120:121], v[144:145] op_sel_hi:[1,1,0]
	v_pk_add_f32 v[128:129], v[128:129], v[128:129] op_sel:[0,1] op_sel_hi:[1,0]
	v_pk_add_f32 v[30:31], v[30:31], v[30:31] op_sel:[0,1] op_sel_hi:[1,0]
	v_mov_b32_e32 v133, v149
	v_mov_b32_e32 v137, v150
	v_mov_b32_e32 v129, v148
	v_mov_b32_e32 v31, v147
	v_pk_add_f32 v[130:131], v[132:133], v[136:137]
	v_pk_add_f32 v[30:31], v[30:31], v[128:129]
	s_nop 0
	v_pk_add_f32 v[30:31], v[30:31], v[130:131]
	s_nop 0
	v_add_f32_e32 v30, v30, v31
	s_nop 0
	s_waitcnt lgkmcnt(0)
	s_nop 1
	v_add_f32_dpp v30, v30, v30 quad_perm:[1,0,3,2] row_mask:0xf bank_mask:0xf
	s_nop 0
	s_waitcnt lgkmcnt(0)
	s_nop 1
	v_add_f32_dpp v30, v30, v30 quad_perm:[2,3,0,1] row_mask:0xf bank_mask:0xf
	s_nop 0
	s_waitcnt lgkmcnt(0)
	s_nop 1
	v_add_f32_dpp v30, v30, v30 row_half_mirror row_mask:0xf bank_mask:0xf
	s_nop 0
	s_waitcnt lgkmcnt(0)
	s_nop 1
	v_add_f32_dpp v30, v30, v30 row_mirror row_mask:0xf bank_mask:0xf
	v_mov_b32_e32 v31, v30
	s_waitcnt lgkmcnt(0)
	s_nop 1
	v_permlane16_swap_b32_e32 v30, v31
	v_add_f32_e32 v30, v30, v31
	v_mov_b32_e32 v31, v30
	s_waitcnt lgkmcnt(0)
	s_nop 1
	v_permlane32_swap_b32_e32 v30, v31
	v_add_f32_e32 v30, v30, v31
	v_fmamk_f32 v30, v30, 0x3a000000, v20
	v_mul_f32_e32 v31, 0x4f800000, v30
	v_cmp_gt_f32_e32 vcc, s29, v30
	s_nop 1
	v_cndmask_b32_e32 v30, v30, v31, vcc
	v_sqrt_f32_e32 v31, v30
	s_nop 0
	v_add_u32_e32 v45, -1, v31
	v_add_u32_e32 v124, 1, v31
	v_fma_f32 v125, -v45, v31, v30
	v_fma_f32 v126, -v124, v31, v30
	v_cmp_ge_f32_e64 s[12:13], 0, v125
	s_nop 1
	v_cndmask_b32_e64 v31, v31, v45, s[12:13]
	v_cmp_lt_f32_e64 s[12:13], 0, v126
	s_nop 1
	v_cndmask_b32_e64 v31, v31, v124, s[12:13]
	v_mul_f32_e32 v45, 0x37800000, v31
	v_cndmask_b32_e32 v31, v31, v45, vcc
	v_cmp_class_f32_e32 vcc, v30, v44
	s_nop 1
	v_cndmask_b32_e32 v31, v31, v30, vcc
	v_div_scale_f32 v30, s[12:13], v31, v31, 1.0
	v_rcp_f32_e32 v124, v30
	v_div_scale_f32 v45, vcc, 1.0, v31, 1.0
	v_fma_f32 v125, -v30, v124, 1.0
	v_fmac_f32_e32 v124, v125, v124
	v_mul_f32_e32 v125, v45, v124
	v_fma_f32 v126, -v30, v125, v45
	v_fmac_f32_e32 v125, v126, v124
	v_fma_f32 v30, -v30, v125, v45
	v_div_fmas_f32 v45, v30, v124, v125
	v_div_fixup_f32 v124, v45, v31, 1.0
	v_pk_mul_f32 v[90:91], v[90:91], v[124:125] op_sel_hi:[1,0]
	v_pk_mul_f32 v[92:93], v[92:93], v[124:125] op_sel_hi:[1,0]
	v_add_co_u32_e32 v30, vcc, s27, v122
	v_pk_mul_f32 v[94:95], v[94:95], v[124:125] op_sel_hi:[1,0]
	v_pk_mul_f32 v[96:97], v[96:97], v[124:125] op_sel_hi:[1,0]
	v_pk_mul_f32 v[98:99], v[98:99], v[124:125] op_sel_hi:[1,0]
	v_pk_mul_f32 v[100:101], v[100:101], v[124:125] op_sel_hi:[1,0]
	v_pk_mul_f32 v[102:103], v[102:103], v[124:125] op_sel_hi:[1,0]
	v_pk_mul_f32 v[104:105], v[104:105], v[124:125] op_sel_hi:[1,0]
	v_pk_mul_f32 v[106:107], v[106:107], v[124:125] op_sel_hi:[1,0]
	v_pk_mul_f32 v[108:109], v[108:109], v[124:125] op_sel_hi:[1,0]
	v_pk_mul_f32 v[110:111], v[110:111], v[124:125] op_sel_hi:[1,0]
	v_pk_mul_f32 v[112:113], v[112:113], v[124:125] op_sel_hi:[1,0]
	v_pk_mul_f32 v[118:119], v[118:119], v[124:125] op_sel_hi:[1,0]
	v_pk_mul_f32 v[120:121], v[120:121], v[124:125] op_sel_hi:[1,0]
	v_pk_mul_f32 v[114:115], v[114:115], v[124:125] op_sel_hi:[1,0]
	v_pk_mul_f32 v[116:117], v[116:117], v[124:125] op_sel_hi:[1,0]
	v_pk_fma_f32 v[2:3], v[2:3], v[92:93], v[14:15]
	v_pk_fma_f32 v[0:1], v[0:1], v[90:91], v[12:13]
	v_addc_co_u32_e32 v31, vcc, 0, v123, vcc
	v_pk_fma_f32 v[6:7], v[6:7], v[96:97], v[10:11]
	v_pk_fma_f32 v[4:5], v[4:5], v[94:95], v[8:9]
	v_pk_fma_f32 v[10:11], v[18:19], v[100:101], v[52:53]
	v_pk_fma_f32 v[8:9], v[16:17], v[98:99], v[50:51]
	v_pk_fma_f32 v[14:15], v[48:49], v[104:105], v[56:57]
	v_pk_fma_f32 v[12:13], v[46:47], v[102:103], v[54:55]
	v_pk_fma_f32 v[18:19], v[60:61], v[108:109], v[68:69]
	v_pk_fma_f32 v[16:17], v[58:59], v[106:107], v[66:67]
	v_pk_fma_f32 v[48:49], v[64:65], v[112:113], v[72:73]
	v_pk_fma_f32 v[46:47], v[62:63], v[110:111], v[70:71]
	v_pk_fma_f32 v[52:53], v[120:121], v[76:77], v[84:85]
	v_pk_fma_f32 v[50:51], v[118:119], v[74:75], v[82:83]
	v_pk_fma_f32 v[56:57], v[116:117], v[80:81], v[88:89]
	v_pk_fma_f32 v[54:55], v[114:115], v[78:79], v[86:87]
	global_store_dwordx4 v[122:123], v[0:3], off
	global_store_dwordx4 v[122:123], v[4:7], off offset:1024
	global_store_dwordx4 v[122:123], v[8:11], off offset:2048
	global_store_dwordx4 v[122:123], v[12:15], off offset:3072
	global_store_dwordx4 v[30:31], v[16:19], off
	global_store_dwordx4 v[30:31], v[46:49], off offset:1024
	global_store_dwordx4 v[30:31], v[50:53], off offset:2048
	global_store_dwordx4 v[30:31], v[54:57], off offset:3072
	s_cbranch_scc1 .LBB0_1327
	s_add_i32 s2, s2, s3
	s_add_i32 s14, s14, s26
	s_cmpk_lt_i32 s2, 0x100
	s_cbranch_scc1 .LBB0_1311
